# MLA attention: next tile's K/V LDS staging issued before the PV MFMAs instead of in front of the barrier
# speedup vs baseline: 1.0104x; 1.0039x over previous
; __device__ __forceinline__ void ffn_conv_item(int tid_in, int b, int strip, bf16_t* h1, const bf16_t* h2, const float* cw, const float* cb, bool st = true) {
;     ...
; #pragma nounroll
;     for (int blk = 0; blk < 16; ++blk) {
;         u32x4 ng4[4], nv4[4];
;         if (blk + 1 < 16) {
; #pragma unroll
;             for (int j = 0; j < 4; ++j) { const size_t o_ = off0 + (size_t)(32 * (blk + 1) + 8 * j + rl) * 5632; ng4[j] = __builtin_nontemporal_load((const u32x4*)(h1 + o_)); nv4[j] = __builtin_nontemporal_load((const u32x4*)(h2 + o_)); }
;         }
.LBB0_25:
	s_waitcnt vmcnt(1)
	v_mov_b64_e32 v[48:49], v[36:37]
	v_mov_b64_e32 v[46:47], v[34:35]
	s_cmp_eq_u32 s34, 0x528000
	v_lshl_add_u64 v[140:141], v[138:139], 0, s[34:35]
	s_cbranch_scc1 .LBB0_24
	v_add_co_u32_e32 v34, vcc, 0x4a58000, v140
	s_nop 1
	v_addc_co_u32_e32 v35, vcc, 0, v141, vcc
	v_add_co_u32_e32 v36, vcc, 0xfa58000, v140
	s_nop 1
	v_addc_co_u32_e32 v37, vcc, 0, v141, vcc
	global_load_dwordx4 v[38:41], v[34:35], off nt
	global_load_dwordx4 v[42:45], v[36:37], off nt
	v_add_co_u32_e32 v34, vcc, 0x4a6e000, v140
	s_nop 1
	v_addc_co_u32_e32 v35, vcc, 0, v141, vcc
	v_add_co_u32_e32 v36, vcc, 0xfa6e000, v140
	s_nop 1
	v_addc_co_u32_e32 v37, vcc, 0, v141, vcc
	global_load_dwordx4 v[50:53], v[34:35], off nt
	global_load_dwordx4 v[54:57], v[36:37], off nt
	v_add_co_u32_e32 v34, vcc, 0x4a84000, v140
	s_nop 1
	v_addc_co_u32_e32 v35, vcc, 0, v141, vcc
	v_add_co_u32_e32 v36, vcc, 0xfa84000, v140
	s_nop 1
	v_addc_co_u32_e32 v37, vcc, 0, v141, vcc
	global_load_dwordx4 v[58:61], v[34:35], off nt
	global_load_dwordx4 v[62:65], v[36:37], off nt
	v_add_co_u32_e32 v34, vcc, 0x4a9a000, v140
	s_nop 1
	v_addc_co_u32_e32 v35, vcc, 0, v141, vcc
	v_add_co_u32_e32 v66, vcc, 0xfa9a000, v140
	s_nop 1
	v_addc_co_u32_e32 v67, vcc, 0, v141, vcc
	global_load_dwordx4 v[34:37], v[34:35], off nt
	s_nop 0
	global_load_dwordx4 v[66:69], v[66:67], off nt
	s_branch .LBB0_24
	s_nop 0
	s_nop 0
	s_nop 0
	s_nop 0
	s_nop 0
	s_nop 0
	s_nop 0
	s_nop 0
	s_nop 0
	s_nop 0
	s_nop 0
	s_nop 0
	s_nop 0
	s_nop 0
	s_nop 0
	s_nop 0
	s_nop 0
	s_nop 0
	s_nop 0
	s_nop 0
	s_nop 0
	s_nop 0
	s_nop 0
	s_nop 0
	s_nop 0
	s_nop 0
	s_nop 0
	s_nop 0
	s_nop 0
	s_nop 0
	s_nop 0
	s_nop 0
	s_nop 0
	s_nop 0
	s_nop 0
	s_nop 0
	s_nop 0
	s_nop 0
	s_nop 0
	s_nop 0
	s_nop 0
	s_nop 0
	s_nop 0
	s_nop 0
	s_nop 0
	s_nop 0
	s_nop 0
	s_nop 0
	s_nop 0
	s_nop 0
	s_nop 0
	s_nop 0
	s_nop 0
	s_nop 0
	s_nop 0
	s_nop 0
	s_nop 0
	s_nop 0
	s_nop 0
	s_nop 0
	s_nop 0
	s_nop 0
	s_nop 0
	s_nop 0
	s_nop 0
	s_nop 0
	s_nop 0
	s_nop 0
	s_nop 0
	s_nop 0
	s_nop 0
	s_nop 0
	s_nop 0
	s_nop 0
	s_nop 0
	s_nop 0
	s_nop 0
	s_nop 0
	s_nop 0
	s_nop 0
	s_nop 0
	s_nop 0
	s_nop 0
	s_nop 0
	s_nop 0
	s_nop 0
	s_nop 0
	s_nop 0
	s_nop 0
	s_nop 0
	s_nop 0
	s_nop 0
	s_nop 0
	s_nop 0
	s_nop 0
	s_nop 0
	s_nop 0
	s_nop 0
	s_nop 0
	s_nop 0
	s_nop 0
	s_nop 0
	s_nop 0
	s_nop 0
	s_nop 0
	s_nop 0
	s_nop 0
	s_nop 0
	s_nop 0
	s_nop 0
	s_nop 0
	s_nop 0
	s_nop 0
	s_nop 0
	s_nop 0
	s_nop 0
	s_nop 0
	s_nop 0
	s_nop 0
	s_nop 0
	s_nop 0
	s_nop 0
	s_nop 0
	s_nop 0
	s_nop 0
	s_nop 0
	s_nop 0
	s_nop 0
	s_nop 0
	s_nop 0
	s_nop 0
	s_nop 0
	s_nop 0
	s_nop 0
	s_nop 0
	s_nop 0
	s_nop 0
	s_nop 0
	s_nop 0
	s_nop 0
	s_nop 0
	s_nop 0
	s_nop 0
	s_nop 0
	s_nop 0
	s_nop 0
	s_nop 0
	s_nop 0
	s_nop 0
	s_nop 0
	s_nop 0
	s_nop 0
	s_nop 0
	s_nop 0
	s_nop 0
	s_nop 0
	s_nop 0
	s_nop 0
	s_nop 0
	s_nop 0
	s_nop 0
	s_nop 0
	s_nop 0
	s_nop 0
	s_nop 0
	s_nop 0
	s_nop 0
	s_nop 0
	s_nop 0
	s_nop 0
	s_nop 0
	s_nop 0
	s_nop 0
	s_nop 0
	s_nop 0
	s_nop 0
	s_nop 0
	s_nop 0
	s_nop 0
	s_nop 0
	s_nop 0
	s_nop 0
	s_nop 0
	s_nop 0
	s_nop 0
	s_nop 0
	s_nop 0
	s_nop 0
	s_nop 0
	s_nop 0
	s_nop 0
	s_nop 0
	s_nop 0
	s_nop 0
	s_nop 0
	s_nop 0
	s_nop 0
	s_nop 0
	s_nop 0
	s_nop 0
	s_nop 0
	s_nop 0
	s_nop 0
	s_nop 0
	s_nop 0
	s_nop 0
	s_nop 0
	s_nop 0
	s_nop 0
	s_nop 0
	s_nop 0
	s_nop 0
	s_nop 0
	s_nop 0
	s_nop 0
	s_nop 0
	s_nop 0
	s_nop 0
	s_nop 0
	s_nop 0
	s_nop 0
	s_nop 0
	s_nop 0
	s_nop 0
	s_nop 0
	s_nop 0
	s_nop 0
	s_nop 0
	s_nop 0
	s_nop 0
	s_nop 0
	s_nop 0
	s_nop 0
	s_nop 0
	s_nop 0
	s_nop 0
	s_nop 0
	s_nop 0
	s_nop 0
	s_nop 0
	s_nop 0
	s_nop 0
	s_nop 0
	s_nop 0
	s_nop 0
	s_nop 0
	s_nop 0
	s_nop 0
	s_nop 0
	s_nop 0
	s_nop 0
	s_nop 0
	s_nop 0
	s_nop 0
	s_nop 0
	s_nop 0
	s_nop 0
	s_nop 0
	s_nop 0
	s_nop 0
	s_nop 0
	s_nop 0
	s_nop 0
	s_nop 0
	s_nop 0
	s_nop 0
	s_nop 0
	s_nop 0
	s_nop 0
	s_nop 0
	s_nop 0
	s_nop 0
	s_nop 0
	s_nop 0
	s_nop 0
	s_nop 0
	s_nop 0
	s_nop 0
	s_nop 0
	s_nop 0
	s_nop 0
	s_nop 0
	s_nop 0
	s_nop 0
	s_nop 0
	s_nop 0
	s_nop 0
	s_nop 0
	s_nop 0
	s_nop 0
	s_nop 0
	s_nop 0
	s_nop 0
	s_nop 0
	s_nop 0
	s_nop 0
	s_nop 0
	s_nop 0
	s_nop 0
	s_nop 0
	s_nop 0
	s_nop 0
	s_nop 0
	s_nop 0
	s_nop 0
	s_nop 0
	s_nop 0
	s_nop 0
	s_nop 0
	s_nop 0
	s_nop 0
	s_nop 0
	s_nop 0
	s_nop 0
	s_nop 0
	s_nop 0
	s_nop 0
	s_nop 0
	s_nop 0
	s_nop 0
	s_nop 0
	s_nop 0
	s_nop 0
	s_nop 0
	s_nop 0
	s_nop 0
	s_nop 0
	s_nop 0
	s_nop 0
	s_nop 0
	s_nop 0
	s_nop 0
	s_nop 0
	s_nop 0
	s_nop 0
	s_nop 0
	s_nop 0
	s_nop 0
	s_nop 0
	s_nop 0
	s_nop 0
	s_nop 0
	s_nop 0
	s_nop 0
	s_nop 0
	s_nop 0
	s_nop 0
	s_nop 0
	s_nop 0
	s_nop 0
	s_nop 0
	s_nop 0
	s_nop 0
	s_nop 0
	s_nop 0
	s_nop 0
	s_nop 0
	s_nop 0
	s_nop 0
	s_nop 0
	s_nop 0
	s_nop 0
	s_nop 0
	s_nop 0
	s_nop 0
	s_nop 0
	s_nop 0
	s_nop 0
	s_nop 0
	s_nop 0
	s_nop 0
	s_nop 0
	s_nop 0
	s_nop 0
	s_nop 0
	s_nop 0
	s_nop 0
	s_nop 0
	s_nop 0
	s_nop 0
	s_nop 0
	s_nop 0
	s_nop 0
	s_nop 0
	s_nop 0
	s_nop 0
	s_nop 0
	s_nop 0
	s_nop 0
	s_nop 0
	s_nop 0
	s_nop 0
	s_nop 0
	s_nop 0
	s_nop 0
	s_nop 0
	s_nop 0
	s_nop 0
	s_nop 0
	s_nop 0
	s_nop 0
	s_nop 0
	s_nop 0
	s_nop 0
	s_nop 0
	s_nop 0
	s_nop 0
	s_nop 0
	s_nop 0
	s_nop 0
	s_nop 0
	s_nop 0
	s_nop 0
	s_nop 0
	s_nop 0
	s_nop 0
	s_nop 0
	s_nop 0
	s_nop 0
	s_nop 0
	s_nop 0
	s_nop 0
	s_nop 0
	s_nop 0
	s_nop 0
	s_nop 0
	s_nop 0
	s_nop 0
	s_nop 0
	s_nop 0
	s_nop 0
	s_nop 0
	s_nop 0
	s_nop 0
	s_nop 0
	s_nop 0
	s_nop 0
	s_nop 0
	s_nop 0
	s_nop 0
	s_nop 0
	s_nop 0
	s_nop 0
	s_nop 0
	s_nop 0
	s_nop 0
	s_nop 0
	s_nop 0
	s_nop 0
	s_nop 0
	s_nop 0
	s_nop 0
	s_nop 0
	s_nop 0
	s_nop 0
	s_nop 0
	s_nop 0
	s_nop 0
	s_nop 0
	s_nop 0
	s_nop 0
	s_nop 0
	s_nop 0
	s_nop 0
	s_nop 0
	s_nop 0
	s_nop 0
	s_nop 0
	s_nop 0
	s_nop 0
	s_nop 0
	s_nop 0
	s_nop 0
	s_nop 0
	s_nop 0
	s_nop 0
	s_nop 0
	s_nop 0
	s_nop 0
	s_nop 0
	s_nop 0
	s_nop 0
	s_nop 0
	s_nop 0
	s_nop 0
	s_nop 0
	s_nop 0
	s_nop 0
	s_nop 0
	s_nop 0
	s_nop 0
	s_nop 0
	s_nop 0
	s_nop 0
	s_nop 0
	s_nop 0
	s_nop 0
	s_nop 0
	s_nop 0
	s_nop 0
	s_nop 0
	s_nop 0
	s_nop 0
	s_nop 0
	s_nop 0
	s_nop 0
	s_nop 0
	s_nop 0
	s_nop 0
	s_nop 0
	s_nop 0
.LBB0_27:
	s_mov_b64 s[12:13], 0
	s_mov_b64 s[16:17], 0
	s_cbranch_execnz .LBB0_95

; #define LAS __attribute__((address_space(3)))
; __device__ __forceinline__ float bflo(unsigned w) { return __uint_as_float(w << 16); }
; __device__ __forceinline__ float bfhi(unsigned w) { return __uint_as_float(w & 0xffff0000u); }
; __device__ __forceinline__ unsigned pk2(float lo, float hi) { return pg8::cvt_pk_bf16(lo, hi); }
; #define LDS_WAIT() asm volatile("s_waitcnt lgkmcnt(0)" ::: "memory")
; __device__ __forceinline__ void mlstm_seq(LAS unsigned char* lds, int tid_in, int b, int h, const bf16_t* z1, const bf16_t* z2a, const float* g_hnorm, bf16_t* yb, const unsigned char* ws) {
;     ...
;         LDS_WAIT(); __builtin_amdgcn_s_barrier(); asm volatile("" ::: "memory");
;         if (tid < 128) NV[tid] = decay * NV[tid] + dn;
; #pragma unroll
;         for (int tb = 0; tb < 2; ++tb) {
;             const int t = 32 * tb + r;
;             const float inv = INV[t];
;             const f32x4 pa = *(const LAS f32x4*)(PR + t * 8), pb = *(const LAS f32x4*)(PR + t * 8 + 4);
;             const float rn = inv * rsqrtf(inv * inv * ((pa[0] + pa[1]) + (pa[2] + pa[3]) + (pb[0] + pb[1]) + (pb[2] + pb[3])) * (1.f / 256.f) + EPSN);
; #pragma unroll
;             for (int g = 0; g < 4; ++g) {
;                 const int dv = 32 * wid + 8 * g + 4 * hh;
;                 u32x2 w; w.x = pk2(Z[tb][4 * g] * rn * bflo(zo[tb][g].x), Z[tb][4 * g + 1] * rn * bfhi(zo[tb][g].x));
;                 w.y = pk2(Z[tb][4 * g + 2] * rn * bflo(zo[tb][g].y), Z[tb][4 * g + 3] * rn * bfhi(zo[tb][g].y));
;                 *(u32x2*)(yb + (tok0 + t) * Z2_LD + h * 256 + dv) = w;
;             }
;         }
.Lml_nostage:
	v_mul_f32_e32 v140, v226, v226
	v_add_f32_e32 v141, v223, v222
	v_add_f32_e32 v142, v224, v225
	v_add_f32_e32 v143, v232, v233
	v_add_f32_e32 v146, v230, v231
	v_add_f32_e32 v141, v141, v142
	v_add_f32_e32 v141, v141, v146
	v_add_f32_e32 v141, v143, v141
	v_mul_f32_e32 v141, v140, v141
	v_fmamk_f32 v141, v141, 0x3b800000, v221
	v_mul_f32_e32 v142, 0x4b800000, v141
	v_cmp_gt_f32_e32 vcc, s77, v141
	s_nop 1
	v_cndmask_b32_e32 v141, v141, v142, vcc
	v_rsq_f32_e32 v141, v141
	s_nop 0
	v_mul_f32_e32 v142, 0x45800000, v141
	v_cndmask_b32_e32 v141, v141, v142, vcc
	v_mul_f32_e32 v145, v226, v141
	v_mul_f32_e32 v82, v82, v145
	v_lshlrev_b32_e32 v140, 16, v180
	v_mul_f32_e32 v83, v83, v145
	v_and_b32_e32 v141, 0xffff0000, v180
	v_mul_f32_e32 v82, v82, v140
	v_mul_f32_e32 v83, v83, v141
	v_mul_f32_e32 v84, v84, v145
	v_lshlrev_b32_e32 v142, 16, v181
	v_mul_f32_e32 v85, v85, v145
	v_and_b32_e32 v143, 0xffff0000, v181
	v_mul_f32_e32 v84, v84, v142
	v_mul_f32_e32 v85, v85, v143
	v_mul_f32_e32 v86, v86, v145
	v_lshlrev_b32_e32 v140, 16, v178
	v_mul_f32_e32 v87, v87, v145
	v_and_b32_e32 v141, 0xffff0000, v178
	v_mul_f32_e32 v86, v86, v140
	v_mul_f32_e32 v87, v87, v141
	v_mul_f32_e32 v88, v88, v145
	v_lshlrev_b32_e32 v142, 16, v179
	v_mul_f32_e32 v89, v89, v145
	v_and_b32_e32 v143, 0xffff0000, v179
	v_mul_f32_e32 v88, v88, v142
	v_mul_f32_e32 v89, v89, v143
	v_cvt_pk_bf16_f32 v82, v82, v83
	v_cvt_pk_bf16_f32 v83, v84, v85
	v_cvt_pk_bf16_f32 v84, v86, v87
	v_cvt_pk_bf16_f32 v85, v88, v89
	s_nop 1
	v_permlane32_swap_b32_e32 v82, v84
	v_permlane32_swap_b32_e32 v83, v85
	v_mul_f32_e32 v90, v90, v145
	v_lshlrev_b32_e32 v140, 16, v174
	v_mul_f32_e32 v91, v91, v145
	v_and_b32_e32 v141, 0xffff0000, v174
	v_mul_f32_e32 v90, v90, v140
	v_mul_f32_e32 v91, v91, v141
	v_mul_f32_e32 v92, v92, v145
	v_lshlrev_b32_e32 v142, 16, v175
	v_mul_f32_e32 v93, v93, v145
	v_and_b32_e32 v143, 0xffff0000, v175
	v_mul_f32_e32 v92, v92, v142
	v_mul_f32_e32 v93, v93, v143
	v_mul_f32_e32 v94, v94, v145
	v_lshlrev_b32_e32 v140, 16, v166
	v_mul_f32_e32 v95, v95, v145
	v_and_b32_e32 v141, 0xffff0000, v166
	v_mul_f32_e32 v94, v94, v140
	v_mul_f32_e32 v95, v95, v141
	v_mul_f32_e32 v96, v96, v145
	v_lshlrev_b32_e32 v142, 16, v167
	v_mul_f32_e32 v97, v97, v145
	v_and_b32_e32 v143, 0xffff0000, v167
	v_mul_f32_e32 v96, v96, v142
	v_mul_f32_e32 v97, v97, v143
	v_cvt_pk_bf16_f32 v90, v90, v91
	v_cvt_pk_bf16_f32 v91, v92, v93
	v_cvt_pk_bf16_f32 v92, v94, v95
	v_cvt_pk_bf16_f32 v93, v96, v97
	s_nop 1
	v_permlane32_swap_b32_e32 v90, v92
	v_permlane32_swap_b32_e32 v91, v93
	s_nop 0
	v_permlane16_swap_b32_e32 v82, v90
	v_permlane16_swap_b32_e32 v83, v91
	v_permlane16_swap_b32_e32 v84, v92
	v_permlane16_swap_b32_e32 v85, v93
	s_add_u32 s12, s66, 0x10800000
	s_addc_u32 s13, s67, 0
	global_store_dwordx4 v168, v[82:85], s[12:13]
	s_add_u32 s12, s66, 0x10820000
	s_addc_u32 s13, s67, 0
	global_store_dwordx4 v168, v[90:93], s[12:13]
	v_mul_f32_e32 v140, v227, v227
	v_add_f32_e32 v141, v235, v234
	v_add_f32_e32 v142, v236, v237
	v_add_f32_e32 v143, v248, v249
	v_add_f32_e32 v146, v246, v247
	v_add_f32_e32 v141, v141, v142
	v_add_f32_e32 v141, v141, v146
	v_add_f32_e32 v141, v143, v141
	v_mul_f32_e32 v141, v140, v141
	v_fmamk_f32 v141, v141, 0x3b800000, v221
	v_mul_f32_e32 v142, 0x4b800000, v141
	v_cmp_gt_f32_e32 vcc, s77, v141
	s_nop 1
	v_cndmask_b32_e32 v141, v141, v142, vcc
	v_rsq_f32_e32 v141, v141
	s_nop 0
	v_mul_f32_e32 v142, 0x45800000, v141
	v_cndmask_b32_e32 v141, v141, v142, vcc
	v_mul_f32_e32 v145, v227, v141
	v_mul_f32_e32 v66, v66, v145
	v_lshlrev_b32_e32 v140, 16, v158
	v_mul_f32_e32 v67, v67, v145
	v_and_b32_e32 v141, 0xffff0000, v158
	v_mul_f32_e32 v66, v66, v140
	v_mul_f32_e32 v67, v67, v141
	v_mul_f32_e32 v68, v68, v145
	v_lshlrev_b32_e32 v142, 16, v159
	v_mul_f32_e32 v69, v69, v145
	v_and_b32_e32 v143, 0xffff0000, v159
	v_mul_f32_e32 v68, v68, v142
	v_mul_f32_e32 v69, v69, v143
	v_mul_f32_e32 v70, v70, v145
	v_lshlrev_b32_e32 v140, 16, v156
	v_mul_f32_e32 v71, v71, v145
	v_and_b32_e32 v141, 0xffff0000, v156
	v_mul_f32_e32 v70, v70, v140
	v_mul_f32_e32 v71, v71, v141
	v_mul_f32_e32 v72, v72, v145
	v_lshlrev_b32_e32 v142, 16, v157
	v_mul_f32_e32 v73, v73, v145
	v_and_b32_e32 v143, 0xffff0000, v157
	v_mul_f32_e32 v72, v72, v142
	v_mul_f32_e32 v73, v73, v143
	v_cvt_pk_bf16_f32 v66, v66, v67
	v_cvt_pk_bf16_f32 v67, v68, v69
	v_cvt_pk_bf16_f32 v68, v70, v71
	v_cvt_pk_bf16_f32 v69, v72, v73
	s_nop 1
	v_permlane32_swap_b32_e32 v66, v68
	v_permlane32_swap_b32_e32 v67, v69
	v_mul_f32_e32 v74, v74, v145
	v_lshlrev_b32_e32 v140, 16, v154
	v_mul_f32_e32 v75, v75, v145
	v_and_b32_e32 v141, 0xffff0000, v154
	v_mul_f32_e32 v74, v74, v140
	v_mul_f32_e32 v75, v75, v141
	v_mul_f32_e32 v76, v76, v145
	v_lshlrev_b32_e32 v142, 16, v155
	v_mul_f32_e32 v77, v77, v145
	v_and_b32_e32 v143, 0xffff0000, v155
	v_mul_f32_e32 v76, v76, v142
	v_mul_f32_e32 v77, v77, v143
	v_mul_f32_e32 v78, v78, v145
	v_lshlrev_b32_e32 v140, 16, v152
	v_mul_f32_e32 v79, v79, v145
	v_and_b32_e32 v141, 0xffff0000, v152
	v_mul_f32_e32 v78, v78, v140
	v_mul_f32_e32 v79, v79, v141
	v_mul_f32_e32 v80, v80, v145
	v_lshlrev_b32_e32 v142, 16, v153
	v_mul_f32_e32 v81, v81, v145
	v_and_b32_e32 v143, 0xffff0000, v153
	v_mul_f32_e32 v80, v80, v142
	v_mul_f32_e32 v81, v81, v143
	v_cvt_pk_bf16_f32 v74, v74, v75
	v_cvt_pk_bf16_f32 v75, v76, v77
	v_cvt_pk_bf16_f32 v76, v78, v79
	v_cvt_pk_bf16_f32 v77, v80, v81
	s_nop 1
	v_permlane32_swap_b32_e32 v74, v76
	v_permlane32_swap_b32_e32 v75, v77
	s_nop 0
	v_permlane16_swap_b32_e32 v66, v74
	v_permlane16_swap_b32_e32 v67, v75
	v_permlane16_swap_b32_e32 v68, v76
	v_permlane16_swap_b32_e32 v69, v77
	s_add_u32 s12, s66, 0x10840000
	s_addc_u32 s13, s67, 0
	global_store_dwordx4 v168, v[66:69], s[12:13]
	s_add_u32 s12, s66, 0x10860000
	s_addc_u32 s13, s67, 0
	global_store_dwordx4 v168, v[74:77], s[12:13]
	s_mov_b64 s[12:13], 0x80000
	v_lshl_add_u64 v[160:161], v[160:161], 0, s[92:93]
	v_lshl_add_u64 v[162:163], v[162:163], 0, s[94:95]
	v_lshl_add_u64 v[150:151], v[150:151], 0, s[12:13]
	v_lshl_add_u64 v[172:173], v[172:173], 0, s[12:13]
	v_lshl_add_u64 v[168:169], v[168:169], 0, s[12:13]
	s_mov_b64 s[12:13], 0x68000
	v_lshl_add_u64 v[170:171], v[170:171], 0, s[16:17]
	v_lshl_add_u64 v[176:177], v[176:177], 0, s[12:13]
	s_add_i32 s14, s14, -1
	s_waitcnt vmcnt(4)
; __device__ __forceinline__ void mlstm_seq(LAS unsigned char* lds, int tid_in, int b, int h, const bf16_t* z1, const bf16_t* z2a, const float* g_hnorm, bf16_t* yb, const unsigned char* ws) {
;     ...
;         u32x2 zo[2][4];
; #pragma unroll
;         for (int tb = 0; tb < 2; ++tb)
; #pragma unroll
;             for (int g = 0; g < 4; ++g) zo[tb][g] = pzo[tb][g];
;         const float wi0 = pwi0, wi1 = pwi1, wq = pwq, eq = peq, dq0 = pdq, dn = pdn;
	v_permlane16_swap_b32_e32 v182, v186
	v_permlane16_swap_b32_e32 v183, v187
	v_permlane16_swap_b32_e32 v184, v188
	v_permlane16_swap_b32_e32 v185, v189
	v_permlane16_swap_b32_e32 v190, v194
	v_permlane16_swap_b32_e32 v191, v195
	v_permlane16_swap_b32_e32 v192, v196
	v_permlane16_swap_b32_e32 v193, v197
	v_permlane32_swap_b32_e32 v182, v184
	v_permlane32_swap_b32_e32 v183, v185
	v_permlane32_swap_b32_e32 v186, v188
	v_permlane32_swap_b32_e32 v187, v189
	v_permlane32_swap_b32_e32 v190, v192
	v_permlane32_swap_b32_e32 v191, v193
	v_permlane32_swap_b32_e32 v194, v196
	v_permlane32_swap_b32_e32 v195, v197
	v_mov_b64_e32 v[180:181], v[182:183]
	v_mov_b64_e32 v[178:179], v[184:185]
	v_mov_b64_e32 v[174:175], v[186:187]
	v_mov_b64_e32 v[166:167], v[188:189]
	v_mov_b64_e32 v[158:159], v[190:191]
	v_mov_b64_e32 v[156:157], v[192:193]
	v_mov_b64_e32 v[154:155], v[194:195]
	v_mov_b64_e32 v[152:153], v[196:197]
	v_mov_b32_e32 v250, v217
	v_mov_b32_e32 v251, v218
	v_mov_b32_e32 v216, v219
	v_mov_b32_e32 v164, v215
	s_cmp_eq_u32 s14, 0
	s_cbranch_scc1 .LBB0_93
	s_waitcnt lgkmcnt(0)
	s_barrier
	s_branch .Lml_loop
.LBB0_93:
	s_mov_b64 s[16:17], -1
	s_mov_b64 s[12:13], 0

; #define MFMA32(a, b, c) __builtin_amdgcn_mfma_f32_32x32x16_bf16((a), (b), (c), 0, 0, 0)
; #define ATT_LDK(buf, g) do { _Pragma("unroll") for (int kk = 0; kk < 2; ++kk) { \
;                 ka[buf][kk][0] = *(const LAS bf16x8*)(Kb + r * KSTR + (2 * (g) + kk) * 32 + hh * 16); ka[buf][kk][1] = *(const LAS bf16x8*)(Kb + (32 + r) * KSTR + (2 * (g) + kk) * 32 + hh * 16); } } while (0)
; #define ATT_LDV(buf, d) do { _Pragma("unroll") for (int kb = 0; kb < 2; ++kb) _Pragma("unroll") for (int s = 0; s < 2; ++s) { \
;                 const LAS unsigned char* p_ = Vb + vlane + (32 * kb + 16 * s) * VSTR + (d) * 64; vl[buf][2 * kb + s] = trread(p_); vh[buf][2 * kb + s] = trread(p_ + 8 * VSTR); } } while (0)
; template <int NKS, bool ALLIN = false> ...
;     ...
;             f32x16 s0, s1;
; #pragma unroll
;             for (int i = 0; i < 16; ++i) { s0[i] = 0.f; s1[i] = 0.f; }
;             bf16x8 ka[2][2][2];
;     ...
;             ATT_LDK(0, 0); ATT_LDK(1, 1);
;             __builtin_amdgcn_sched_barrier(0);
; #pragma unroll
;             for (int g = 0; g < NKS / 2; ++g) {
; #pragma unroll
;                 for (int kk = 0; kk < 2; ++kk) { s0 = MFMA32(ka[g & 1][kk][0], qf[2 * g + kk], s0); s1 = MFMA32(ka[g & 1][kk][1], qf[2 * g + kk], s1); }
;                 __builtin_amdgcn_sched_barrier(0);
;                 if (g + 2 < NKS / 2) { ATT_LDK(g & 1, g + 2); __builtin_amdgcn_sched_barrier(0); }
;             }
;     ...
;             s16x4 vl[2][4], vh[2][4];
;     ...
;             ATT_LDV(0, 0); ATT_LDV(1, 1);
;             __builtin_amdgcn_sched_barrier(0);
;             float mx = -INFINITY;
; #pragma unroll
;             for (int i = 0; i < 16; ++i) mx = fmaxf(mx, fmaxf(s0[i], s1[i]));
;             mx = fmaxf(mx, __shfl_xor(mx, 32)) * c2;
.LBB0_108:
	s_and_b32 s19, s22, 1
	s_mul_i32 s22, s19, 0x6400
	v_add_u32_e32 v0, s22, v215
	ds_read_b128 v[2:5], v0
	ds_read_b128 v[6:9], v0 offset:32
	ds_read_b128 v[10:13], v0 offset:12800
	ds_read_b128 v[180:183], v0 offset:12832
	ds_read_b128 v[184:187], v0 offset:64
	ds_read_b128 v[188:191], v0 offset:96
	ds_read_b128 v[192:195], v0 offset:12864
	ds_read_b128 v[196:199], v0 offset:12896
	s_mulk_i32 s19, 0x5000
	s_waitcnt lgkmcnt(7)
	v_mfma_f32_32x32x16_bf16 v[96:111], v[2:5], v[132:135], 0
	s_waitcnt lgkmcnt(5)
	v_mfma_f32_32x32x16_bf16 v[80:95], v[10:13], v[132:135], 0
	v_mfma_f32_32x32x16_bf16 v[96:111], v[6:9], v[136:139], v[96:111]
	s_waitcnt lgkmcnt(4)
	v_mfma_f32_32x32x16_bf16 v[80:95], v[180:183], v[136:139], v[80:95]
	ds_read_b128 v[2:5], v0 offset:128
	ds_read_b128 v[6:9], v0 offset:160
	ds_read_b128 v[10:13], v0 offset:12928
	ds_read_b128 v[180:183], v0 offset:12960
	s_waitcnt lgkmcnt(7)
	v_mfma_f32_32x32x16_bf16 v[96:111], v[184:187], v[140:143], v[96:111]
	s_waitcnt lgkmcnt(5)
	v_mfma_f32_32x32x16_bf16 v[80:95], v[192:195], v[140:143], v[80:95]
	v_mfma_f32_32x32x16_bf16 v[96:111], v[188:191], v[144:147], v[96:111]
	s_waitcnt lgkmcnt(4)
	v_mfma_f32_32x32x16_bf16 v[80:95], v[196:199], v[144:147], v[80:95]
	ds_read_b128 v[184:187], v0 offset:192
	ds_read_b128 v[188:191], v0 offset:224
	ds_read_b128 v[192:195], v0 offset:12992
	ds_read_b128 v[196:199], v0 offset:13024
	s_waitcnt lgkmcnt(7)
	v_mfma_f32_32x32x16_bf16 v[96:111], v[2:5], v[148:151], v[96:111]
	s_waitcnt lgkmcnt(5)
	v_mfma_f32_32x32x16_bf16 v[80:95], v[10:13], v[148:151], v[80:95]
	v_mfma_f32_32x32x16_bf16 v[96:111], v[6:9], v[152:155], v[96:111]
	s_waitcnt lgkmcnt(4)
	v_mfma_f32_32x32x16_bf16 v[80:95], v[180:183], v[152:155], v[80:95]
	ds_read_b128 v[2:5], v0 offset:256
	ds_read_b128 v[6:9], v0 offset:288
	ds_read_b128 v[10:13], v0 offset:13056
	ds_read_b128 v[180:183], v0 offset:13088
	s_waitcnt lgkmcnt(7)
	v_mfma_f32_32x32x16_bf16 v[96:111], v[184:187], v[156:159], v[96:111]
	s_waitcnt lgkmcnt(5)
	v_mfma_f32_32x32x16_bf16 v[80:95], v[192:195], v[156:159], v[80:95]
	v_mfma_f32_32x32x16_bf16 v[96:111], v[188:191], v[160:163], v[96:111]
	s_waitcnt lgkmcnt(4)
	v_mfma_f32_32x32x16_bf16 v[80:95], v[196:199], v[160:163], v[80:95]
	ds_read_b128 v[184:187], v0 offset:320
	ds_read_b128 v[188:191], v0 offset:352
	ds_read_b128 v[192:195], v0 offset:13120
	ds_read_b128 v[196:199], v0 offset:13152
	s_waitcnt lgkmcnt(7)
	v_mfma_f32_32x32x16_bf16 v[96:111], v[2:5], v[164:167], v[96:111]
	s_waitcnt lgkmcnt(5)
	v_mfma_f32_32x32x16_bf16 v[80:95], v[10:13], v[164:167], v[80:95]
	v_mfma_f32_32x32x16_bf16 v[96:111], v[6:9], v[168:171], v[96:111]
	s_waitcnt lgkmcnt(4)
	v_mfma_f32_32x32x16_bf16 v[80:95], v[180:183], v[168:171], v[80:95]
	s_waitcnt lgkmcnt(3)
	v_mfma_f32_32x32x16_bf16 v[96:111], v[184:187], v[172:175], v[96:111]
	s_waitcnt lgkmcnt(1)
	v_mfma_f32_32x32x16_bf16 v[80:95], v[192:195], v[172:175], v[80:95]
	v_mfma_f32_32x32x16_bf16 v[96:111], v[188:191], v[176:179], v[96:111]
	s_waitcnt lgkmcnt(0)
	v_mfma_f32_32x32x16_bf16 v[80:95], v[196:199], v[176:179], v[80:95]
	v_add_u32_e32 v222, s19, v213
	v_add_u32_e32 v218, 0xc800, v222
	ds_read_b64_tr_b16 v[184:185], v222 offset:51200
	ds_read_b64_tr_b16 v[186:187], v222 offset:53760
	ds_read_b64_tr_b16 v[182:183], v222 offset:53824
	ds_read_b64_tr_b16 v[180:181], v222 offset:51264
	ds_read_b64_tr_b16 v[196:197], v222 offset:56320
	ds_read_b64_tr_b16 v[198:199], v222 offset:58880
	ds_read_b64_tr_b16 v[12:13], v222 offset:58944
	ds_read_b64_tr_b16 v[10:11], v222 offset:56384
	ds_read_b64_tr_b16 v[192:193], v222 offset:61440
	ds_read_b64_tr_b16 v[194:195], v222 offset:64000
	ds_read_b64_tr_b16 v[8:9], v222 offset:64064
	ds_read_b64_tr_b16 v[6:7], v222 offset:61504
	ds_read_b64_tr_b16 v[188:189], v218 offset:15360
	ds_read_b64_tr_b16 v[190:191], v218 offset:17920
	ds_read_b64_tr_b16 v[4:5], v218 offset:17984
	ds_read_b64_tr_b16 v[2:3], v218 offset:15424
	v_max_f32_e32 v0, v80, v80
	v_max_f32_e32 v14, v96, v96
	v_max_f32_e32 v0, v14, v0
	v_max_f32_e32 v14, v81, v81
	v_max_f32_e32 v15, v97, v97
	v_max_f32_e32 v14, v15, v14
	v_max3_f32 v0, v0, s73, v14
	v_max_f32_e32 v14, v82, v82
	v_max_f32_e32 v15, v98, v98
	v_max_f32_e32 v14, v15, v14
	v_max_f32_e32 v15, v83, v83
	v_max_f32_e32 v223, v99, v99
	v_max_f32_e32 v15, v223, v15
	v_max3_f32 v0, v0, v14, v15
	v_max_f32_e32 v14, v84, v84
	v_max_f32_e32 v15, v100, v100
	v_max_f32_e32 v14, v15, v14
	v_max_f32_e32 v15, v85, v85
	v_max_f32_e32 v223, v101, v101
	v_max_f32_e32 v15, v223, v15
	v_max3_f32 v0, v0, v14, v15
	v_max_f32_e32 v14, v86, v86
	v_max_f32_e32 v15, v102, v102
	v_max_f32_e32 v14, v15, v14
	v_max_f32_e32 v15, v87, v87
	v_max_f32_e32 v223, v103, v103
	v_max_f32_e32 v15, v223, v15
	v_max3_f32 v0, v0, v14, v15
	v_max_f32_e32 v14, v88, v88
	v_max_f32_e32 v15, v104, v104
	v_max_f32_e32 v14, v15, v14
	v_max_f32_e32 v15, v89, v89
	v_max_f32_e32 v223, v105, v105
	v_max_f32_e32 v15, v223, v15
	v_max3_f32 v0, v0, v14, v15
	v_max_f32_e32 v14, v90, v90
	v_max_f32_e32 v15, v106, v106
	v_max_f32_e32 v14, v15, v14
	v_max_f32_e32 v15, v91, v91
	v_max_f32_e32 v223, v107, v107
	v_max_f32_e32 v15, v223, v15
	v_max3_f32 v0, v0, v14, v15
	v_max_f32_e32 v14, v92, v92
	v_max_f32_e32 v15, v108, v108
	v_max_f32_e32 v14, v15, v14
	v_max_f32_e32 v15, v93, v93
	v_max_f32_e32 v223, v109, v109
	v_max_f32_e32 v15, v223, v15
	v_max3_f32 v0, v0, v14, v15
	v_max_f32_e32 v14, v94, v94
	v_max_f32_e32 v15, v110, v110
	v_max_f32_e32 v14, v15, v14
	v_max_f32_e32 v15, v95, v95
	v_max_f32_e32 v223, v111, v111
	v_max_f32_e32 v15, v223, v15
	v_max3_f32 v0, v0, v14, v15
	v_and_b32_e32 v15, 64, v220
	v_xor_b32_e32 v14, 32, v220
	v_add_u32_e32 v15, 64, v15
	v_cmp_lt_i32_e32 vcc, v14, v15
	s_nop 1
	v_cndmask_b32_e32 v14, v220, v14, vcc
	v_lshlrev_b32_e32 v14, 2, v14
	ds_bpermute_b32 v14, v14, v0
	s_waitcnt lgkmcnt(0)
; template <int NKS, bool ALLIN = false> ...
;     ...
;             float mx = -INFINITY;
; #pragma unroll
;             for (int i = 0; i < 16; ++i) mx = fmaxf(mx, fmaxf(s0[i], s1[i]));
;             mx = fmaxf(mx, __shfl_xor(mx, 32)) * c2;
;             const float mnew = fmaxf(mrun, mx), alpha = __builtin_amdgcn_exp2f(mrun - mnew); mrun = mnew;
;             float ls = 0.f;
; #pragma unroll
;             for (int i = 0; i < 16; ++i) { s0[i] = __builtin_amdgcn_exp2f(fmaf(s0[i], c2, -mnew)); s1[i] = __builtin_amdgcn_exp2f(fmaf(s1[i], c2, -mnew)); ls += s0[i] + s1[i]; }
;             lrun = lrun * alpha + ls;
; #pragma unroll
;             for (int d = 0; d < 4; ++d)
; #pragma unroll
;                 for (int i = 0; i < 16; ++i) o[d][i] *= alpha;
;             bf16x8 pf[4];
;             pf[0] = packacc8(s0, 0); pf[1] = packacc8(s0, 8); pf[2] = packacc8(s1, 0); pf[3] = packacc8(s1, 8);
	v_max_f32_e32 v14, v14, v14
	v_max_f32_e32 v0, v0, v14
	v_mul_f32_e32 v0, 0x3dd53b94, v0
	v_max_f32_e32 v14, v219, v219
	v_max_f32_e32 v223, v14, v0
	v_fma_f32 v14, v98, s80, -v223
	v_exp_f32_e32 v234, v14
	v_fma_f32 v14, v82, s80, -v223
	v_fma_f32 v0, v96, s80, -v223
	v_exp_f32_e32 v235, v14
	v_fma_f32 v14, v99, s80, -v223
	v_exp_f32_e32 v224, v0
	v_fma_f32 v0, v80, s80, -v223
	v_exp_f32_e32 v236, v14
	v_fma_f32 v14, v83, s80, -v223
	v_exp_f32_e32 v225, v0
	v_fma_f32 v0, v97, s80, -v223
	v_exp_f32_e32 v237, v14
	v_fma_f32 v14, v100, s80, -v223
	v_exp_f32_e32 v226, v0
	v_fma_f32 v0, v81, s80, -v223
	v_exp_f32_e32 v81, v14
	v_fma_f32 v14, v84, s80, -v223
	v_exp_f32_e32 v15, v14
	v_fma_f32 v14, v101, s80, -v223
	v_fma_f32 v82, v102, s80, -v223
	v_exp_f32_e32 v80, v14
	v_fma_f32 v14, v85, s80, -v223
	v_exp_f32_e32 v85, v82
	v_fma_f32 v82, v86, s80, -v223
	v_fma_f32 v86, v104, s80, -v223
	v_exp_f32_e32 v101, v86
	v_fma_f32 v86, v88, s80, -v223
	v_fma_f32 v88, v106, s80, -v223
	v_exp_f32_e32 v83, v82
	v_fma_f32 v82, v103, s80, -v223
	v_exp_f32_e32 v103, v88
	v_fma_f32 v88, v90, s80, -v223
	v_exp_f32_e32 v84, v82
	v_fma_f32 v82, v87, s80, -v223
	v_exp_f32_e32 v87, v86
	v_fma_f32 v86, v105, s80, -v223
	v_exp_f32_e32 v105, v88
	v_fma_f32 v88, v107, s80, -v223
	v_exp_f32_e32 v102, v88
	v_fma_f32 v88, v91, s80, -v223
	v_exp_f32_e32 v227, v0
	v_exp_f32_e32 v104, v88
	v_fma_f32 v88, v108, s80, -v223
	v_exp_f32_e32 v107, v88
	v_fma_f32 v88, v92, s80, -v223
	v_exp_f32_e32 v231, v88
	v_fma_f32 v88, v109, s80, -v223
	v_sub_f32_e32 v0, v219, v223
	v_add_f32_e32 v219, v224, v225
	v_exp_f32_e32 v14, v14
	v_exp_f32_e32 v106, v88
	v_fma_f32 v88, v93, s80, -v223
	v_add_f32_e32 v229, v226, v227
	v_exp_f32_e32 v230, v88
	v_fma_f32 v88, v110, s80, -v223
	v_add_f32_e32 v110, 0, v219
	v_exp_f32_e32 v82, v82
	v_add_f32_e32 v238, v234, v235
	v_add_f32_e32 v110, v229, v110
	v_add_f32_e32 v239, v236, v237
	v_exp_f32_e32 v100, v86
	v_fma_f32 v86, v89, s80, -v223
	v_add_f32_e32 v110, v238, v110
	v_pk_add_f32 v[96:97], v[80:81], v[14:15]
	v_exp_f32_e32 v86, v86
	v_add_f32_e32 v110, v239, v110
	v_exp_f32_e32 v109, v88
	v_fma_f32 v88, v94, s80, -v223
	v_add_f32_e32 v97, v97, v110
	v_pk_add_f32 v[98:99], v[84:85], v[82:83]
	v_exp_f32_e32 v233, v88
	v_fma_f32 v88, v111, s80, -v223
	v_add_f32_e32 v96, v96, v97
	v_exp_f32_e32 v108, v88
	v_fma_f32 v88, v95, s80, -v223
	v_add_f32_e32 v96, v99, v96
	v_exp_f32_e32 v232, v88
	v_pk_add_f32 v[88:89], v[100:101], v[86:87]
	v_add_f32_e32 v96, v98, v96
	v_add_f32_e32 v89, v89, v96
	v_pk_add_f32 v[90:91], v[102:103], v[104:105]
	v_add_f32_e32 v88, v88, v89
	v_add_f32_e32 v88, v91, v88
	v_exp_f32_e32 v0, v0
	v_pk_add_f32 v[92:93], v[106:107], v[230:231]
	v_add_f32_e32 v88, v90, v88
	v_add_f32_e32 v88, v93, v88
	v_pk_add_f32 v[94:95], v[108:109], v[232:233]
	v_add_f32_e32 v88, v92, v88
	v_add_f32_e32 v88, v95, v88
	v_pk_mul_f32 v[78:79], v[78:79], v[0:1] op_sel_hi:[1,0]
	v_pk_mul_f32 v[76:77], v[76:77], v[0:1] op_sel_hi:[1,0]
	v_pk_mul_f32 v[74:75], v[74:75], v[0:1] op_sel_hi:[1,0]
	v_pk_mul_f32 v[72:73], v[72:73], v[0:1] op_sel_hi:[1,0]
	v_pk_mul_f32 v[70:71], v[70:71], v[0:1] op_sel_hi:[1,0]
	v_pk_mul_f32 v[68:69], v[68:69], v[0:1] op_sel_hi:[1,0]
	v_pk_mul_f32 v[66:67], v[66:67], v[0:1] op_sel_hi:[1,0]
	v_pk_mul_f32 v[64:65], v[64:65], v[0:1] op_sel_hi:[1,0]
	v_pk_mul_f32 v[62:63], v[62:63], v[0:1] op_sel_hi:[1,0]
	v_pk_mul_f32 v[60:61], v[60:61], v[0:1] op_sel_hi:[1,0]
	v_pk_mul_f32 v[58:59], v[58:59], v[0:1] op_sel_hi:[1,0]
	v_pk_mul_f32 v[56:57], v[56:57], v[0:1] op_sel_hi:[1,0]
	v_pk_mul_f32 v[54:55], v[54:55], v[0:1] op_sel_hi:[1,0]
	v_pk_mul_f32 v[52:53], v[52:53], v[0:1] op_sel_hi:[1,0]
	v_pk_mul_f32 v[50:51], v[50:51], v[0:1] op_sel_hi:[1,0]
	v_pk_mul_f32 v[48:49], v[48:49], v[0:1] op_sel_hi:[1,0]
	v_pk_mul_f32 v[46:47], v[46:47], v[0:1] op_sel_hi:[1,0]
	v_pk_mul_f32 v[44:45], v[44:45], v[0:1] op_sel_hi:[1,0]
	v_pk_mul_f32 v[42:43], v[42:43], v[0:1] op_sel_hi:[1,0]
	v_pk_mul_f32 v[40:41], v[40:41], v[0:1] op_sel_hi:[1,0]
	v_pk_mul_f32 v[38:39], v[38:39], v[0:1] op_sel_hi:[1,0]
	v_pk_mul_f32 v[36:37], v[36:37], v[0:1] op_sel_hi:[1,0]
	v_pk_mul_f32 v[34:35], v[34:35], v[0:1] op_sel_hi:[1,0]
	v_pk_mul_f32 v[32:33], v[32:33], v[0:1] op_sel_hi:[1,0]
	v_pk_mul_f32 v[30:31], v[30:31], v[0:1] op_sel_hi:[1,0]
	v_pk_mul_f32 v[28:29], v[28:29], v[0:1] op_sel_hi:[1,0]
	v_pk_mul_f32 v[26:27], v[26:27], v[0:1] op_sel_hi:[1,0]
	v_pk_mul_f32 v[24:25], v[24:25], v[0:1] op_sel_hi:[1,0]
	v_pk_mul_f32 v[22:23], v[22:23], v[0:1] op_sel_hi:[1,0]
	v_pk_mul_f32 v[20:21], v[20:21], v[0:1] op_sel_hi:[1,0]
	v_pk_mul_f32 v[18:19], v[18:19], v[0:1] op_sel_hi:[1,0]
	v_pk_mul_f32 v[16:17], v[16:17], v[0:1] op_sel_hi:[1,0]
	v_add_f32_e32 v219, v94, v88
	v_cvt_pk_bf16_f32 v88, v224, v226
	v_cvt_pk_bf16_f32 v89, v234, v236
	v_cvt_pk_bf16_f32 v90, v81, v80
	v_cvt_pk_bf16_f32 v91, v85, v84
	v_cvt_pk_bf16_f32 v92, v101, v100
	v_cvt_pk_bf16_f32 v93, v103, v102
	v_cvt_pk_bf16_f32 v94, v107, v106
	v_cvt_pk_bf16_f32 v95, v109, v108
	v_cvt_pk_bf16_f32 v96, v225, v227
	v_cvt_pk_bf16_f32 v97, v235, v237
	v_cvt_pk_bf16_f32 v98, v15, v14
	v_cvt_pk_bf16_f32 v99, v83, v82
	v_cvt_pk_bf16_f32 v80, v87, v86
	v_cvt_pk_bf16_f32 v81, v105, v104
	v_cvt_pk_bf16_f32 v82, v231, v230
	v_cvt_pk_bf16_f32 v83, v233, v232
	s_andn2_b64 vcc, exec, s[16:17]
	s_cbranch_vccnz .Latt_st_skip
	s_and_b32 s19, s18, 1
	s_mul_i32 s23, s19, 0x6400
	v_add3_u32 v240, s23, v205, v202
	s_mulk_i32 s19, 0xec00
	s_waitcnt vmcnt(4)
	ds_write_b128 v240, v[112:115]
	v_add3_u32 v240, s23, v216, v202
	s_add_i32 s19, s23, s19
	s_waitcnt vmcnt(3)
	ds_write_b128 v240, v[116:119]
	v_add3_u32 v240, s23, v211, v204
	s_waitcnt vmcnt(2)
	ds_write_b128 v240, v[120:123] offset:256
	v_add3_u32 v240, s19, v212, v202
	s_waitcnt vmcnt(1)
	ds_write_b128 v240, v[124:127] offset:51200
	v_add3_u32 v240, s19, v217, v202
	s_waitcnt vmcnt(0)
	ds_write_b128 v240, v[128:131] offset:51200
; #define MFMA32(a, b, c) __builtin_amdgcn_mfma_f32_32x32x16_bf16((a), (b), (c), 0, 0, 0)
; __device__ __forceinline__ bf16x8 cat44(s16x4 lo, s16x4 hi) { return (bf16x8){lo[0], lo[1], lo[2], lo[3], hi[0], hi[1], hi[2], hi[3]}; }
; #define ATT_LDV(buf, d) do { _Pragma("unroll") for (int kb = 0; kb < 2; ++kb) _Pragma("unroll") for (int s = 0; s < 2; ++s) { \
;                 const LAS unsigned char* p_ = Vb + vlane + (32 * kb + 16 * s) * VSTR + (d) * 64; vl[buf][2 * kb + s] = trread(p_); vh[buf][2 * kb + s] = trread(p_ + 8 * VSTR); } } while (0)
; template <int NKS, bool ALLIN = false> ...
;     ...
; #pragma unroll
;             for (int d = 0; d < 4; ++d) {
; #pragma unroll
;                 for (int j = 0; j < 4; ++j) o[d] = MFMA32(cat44(vl[d & 1][j], vh[d & 1][j]), pf[j], o[d]);
;                 __builtin_amdgcn_sched_barrier(0);
;                 if (d + 2 < 4) { ATT_LDV(d & 1, d + 2); __builtin_amdgcn_sched_barrier(0); }
;             }
;     ...
;         }
;         if constexpr (!ALLIN) { if (t + 1 < NT) ATT_STORE((t + 1) & 1); __syncthreads(); }
.Latt_st_skip:
	s_nop 0
	v_mfma_f32_32x32x16_bf16 v[64:79], v[184:187], v[88:91], v[64:79]
	v_mfma_f32_32x32x16_bf16 v[64:79], v[196:199], v[92:95], v[64:79]
	v_mfma_f32_32x32x16_bf16 v[64:79], v[192:195], v[96:99], v[64:79]
	v_mfma_f32_32x32x16_bf16 v[64:79], v[188:191], v[80:83], v[64:79]
	ds_read_b64_tr_b16 v[84:85], v222 offset:51328
	ds_read_b64_tr_b16 v[86:87], v222 offset:53888
	ds_read_b64_tr_b16 v[100:101], v222 offset:56448
	ds_read_b64_tr_b16 v[102:103], v222 offset:59008
	ds_read_b64_tr_b16 v[104:105], v222 offset:61568
	ds_read_b64_tr_b16 v[106:107], v222 offset:64128
	ds_read_b64_tr_b16 v[108:109], v218 offset:15488
	ds_read_b64_tr_b16 v[110:111], v218 offset:18048
	v_mfma_f32_32x32x16_bf16 v[48:63], v[180:183], v[88:91], v[48:63]
	v_mfma_f32_32x32x16_bf16 v[48:63], v[10:13], v[92:95], v[48:63]
	v_mfma_f32_32x32x16_bf16 v[48:63], v[6:9], v[96:99], v[48:63]
	v_mfma_f32_32x32x16_bf16 v[48:63], v[2:5], v[80:83], v[48:63]
	ds_read_b64_tr_b16 v[2:3], v222 offset:51392
	ds_read_b64_tr_b16 v[4:5], v222 offset:53952
	ds_read_b64_tr_b16 v[6:7], v222 offset:56512
	ds_read_b64_tr_b16 v[8:9], v222 offset:59072
	ds_read_b64_tr_b16 v[10:11], v222 offset:61632
	ds_read_b64_tr_b16 v[12:13], v222 offset:64192
	ds_read_b64_tr_b16 v[180:181], v218 offset:15552
	ds_read_b64_tr_b16 v[182:183], v218 offset:18112
	s_waitcnt lgkmcnt(14)
	v_mfma_f32_32x32x16_bf16 v[32:47], v[84:87], v[88:91], v[32:47]
	s_waitcnt lgkmcnt(12)
	v_mfma_f32_32x32x16_bf16 v[32:47], v[100:103], v[92:95], v[32:47]
	s_waitcnt lgkmcnt(10)
	v_mfma_f32_32x32x16_bf16 v[32:47], v[104:107], v[96:99], v[32:47]
	s_waitcnt lgkmcnt(8)
	v_mfma_f32_32x32x16_bf16 v[32:47], v[108:111], v[80:83], v[32:47]
	s_waitcnt lgkmcnt(6)
	v_mfma_f32_32x32x16_bf16 v[16:31], v[2:5], v[88:91], v[16:31]
	s_waitcnt lgkmcnt(4)
	v_mfma_f32_32x32x16_bf16 v[16:31], v[6:9], v[92:95], v[16:31]
	s_waitcnt lgkmcnt(2)
	v_mfma_f32_32x32x16_bf16 v[16:31], v[10:13], v[96:99], v[16:31]
	s_waitcnt lgkmcnt(0)
	v_mfma_f32_32x32x16_bf16 v[16:31], v[180:183], v[80:83], v[16:31]
	v_fmac_f32_e32 v219, v214, v0
	v_mov_b32_e32 v214, v219
	v_mov_b32_e32 v219, v223
	s_branch .LBB0_105
